# plus attention unit prologue: Q/K/kmax loads hoisted into one round trip
# baseline (speedup 1.0000x reference)
.LBB0_354:
	s_or_b64 exec, exec, s[0:1]
	s_lshl_b32 s1, s2, 7
	s_and_b32 s14, s1, 0xf80
	s_ashr_i32 s15, s2, 5
	s_add_i32 s38, s14, s40
	s_sub_i32 s0, 3, s15
	v_add_u32_e32 v140, s38, v126
	v_lshlrev_b64 v[0:1], 10, v[140:141]
	s_lshl_b32 s52, s0, 7
	v_lshl_add_u64 v[2:3], s[24:25], 0, v[0:1]
	s_lshl_b64 s[12:13], s[52:53], 1
	v_lshl_add_u64 v[0:1], s[66:67], 0, v[0:1]
	v_lshl_add_u64 v[2:3], v[2:3], 0, s[12:13]
	v_lshlrev_b64 v[4:5], 1, v[102:103]
	v_lshl_add_u64 v[0:1], v[0:1], 0, s[12:13]
	v_lshl_add_u64 v[12:13], v[2:3], 0, v[4:5]
	v_lshl_add_u64 v[16:17], v[0:1], 0, v[4:5]
	flat_load_dwordx4 v[0:3], v[12:13]
	flat_load_dwordx4 v[4:7], v[16:17]
	s_lshl_b32 s0, s0, 1
	s_add_i32 s0, s16, s0
	s_mov_b32 s1, s53
	s_lshl_b64 s[0:1], s[0:1], 2
	v_readlane_b32 s10, v252, 36
	v_readlane_b32 s11, v252, 37
	s_add_u32 s0, s10, s0
	s_addc_u32 s1, s11, s1
	flat_load_dwordx4 v[24:27], v[16:17] offset:128
	v_mov_b64_e32 v[174:175], s[0:1]
	global_load_dwordx4 v[160:163], v[12:13], off offset:64
	global_load_dwordx4 v[164:167], v[16:17], off offset:64
	global_load_dwordx4 v[168:171], v[16:17], off offset:192
	global_load_dwordx2 v[172:173], v[174:175], off
	global_load_dwordx4 v[176:179], v[12:13], off offset:128
	global_load_dwordx4 v[180:183], v[12:13], off offset:192
	s_waitcnt vmcnt(0) lgkmcnt(0)
	v_lshlrev_b32_e32 v8, 16, v0
	v_lshlrev_b32_e32 v9, 16, v4
	v_fma_f32 v18, v8, v9, 0
	v_and_b32_e32 v9, 0xffff0000, v0
	v_mul_f32_e32 v19, v9, v9
	v_and_b32_e32 v4, 0xffff0000, v4
	v_fmac_f32_e32 v19, v8, v8
	v_fmac_f32_e32 v18, v9, v4
	v_lshlrev_b32_e32 v4, 16, v1
	v_lshlrev_b32_e32 v8, 16, v5
	v_fmac_f32_e32 v19, v4, v4
	v_fmac_f32_e32 v18, v4, v8
	v_and_b32_e32 v4, 0xffff0000, v1
	v_and_b32_e32 v5, 0xffff0000, v5
	v_fmac_f32_e32 v19, v4, v4
	v_fmac_f32_e32 v18, v4, v5
	v_lshlrev_b32_e32 v4, 16, v2
	v_lshlrev_b32_e32 v5, 16, v6
	v_fmac_f32_e32 v19, v4, v4
	v_fmac_f32_e32 v18, v4, v5
	v_and_b32_e32 v4, 0xffff0000, v2
	v_and_b32_e32 v5, 0xffff0000, v6
	v_fmac_f32_e32 v19, v4, v4
	v_fmac_f32_e32 v18, v4, v5
	v_lshlrev_b32_e32 v4, 16, v3
	v_lshlrev_b32_e32 v5, 16, v7
	v_fmac_f32_e32 v19, v4, v4
	v_fmac_f32_e32 v18, v4, v5
	v_and_b32_e32 v4, 0xffff0000, v3
	v_and_b32_e32 v5, 0xffff0000, v7
	v_fmac_f32_e32 v19, v4, v4
	v_fmac_f32_e32 v18, v4, v5
	v_mov_b64_e32 v[4:5], v[160:161]
	v_mov_b64_e32 v[6:7], v[162:163]
	v_mov_b64_e32 v[8:9], v[164:165]
	v_mov_b64_e32 v[10:11], v[166:167]
	v_lshlrev_b32_e32 v14, 16, v4
	v_lshlrev_b32_e32 v15, 16, v8
	v_fmac_f32_e32 v19, v14, v14
	v_fmac_f32_e32 v18, v14, v15
	v_and_b32_e32 v14, 0xffff0000, v4
	v_and_b32_e32 v8, 0xffff0000, v8
	v_fmac_f32_e32 v19, v14, v14
	v_fmac_f32_e32 v18, v14, v8
	v_lshlrev_b32_e32 v8, 16, v5
	v_lshlrev_b32_e32 v14, 16, v9
	v_fmac_f32_e32 v19, v8, v8
	v_fmac_f32_e32 v18, v8, v14
	v_and_b32_e32 v8, 0xffff0000, v5
	v_and_b32_e32 v9, 0xffff0000, v9
	v_fmac_f32_e32 v19, v8, v8
	v_fmac_f32_e32 v18, v8, v9
	v_lshlrev_b32_e32 v20, 16, v10
	v_and_b32_e32 v9, 0xffff0000, v6
	v_lshlrev_b32_e32 v8, 16, v6
	v_pk_mul_f32 v[14:15], v[8:9], v[8:9]
	v_fmac_f32_e32 v18, v8, v20
	v_and_b32_e32 v8, 0xffff0000, v10
	v_add_f32_e32 v14, v19, v14
	v_fmac_f32_e32 v18, v9, v8
	v_and_b32_e32 v9, 0xffff0000, v7
	v_lshlrev_b32_e32 v8, 16, v7
	v_add_f32_e32 v19, v14, v15
	v_pk_mul_f32 v[14:15], v[8:9], v[8:9]
	v_lshlrev_b32_e32 v10, 16, v11
	v_add_f32_e32 v14, v19, v14
	v_fmac_f32_e32 v18, v8, v10
	v_add_f32_e32 v8, v14, v15
	v_and_b32_e32 v10, 0xffff0000, v11
	v_fmac_f32_e32 v18, v9, v10
	ds_bpermute_b32 v9, v127, v8
	v_lshlrev_b32_e32 v15, 16, v24
	s_waitcnt lgkmcnt(0)
	v_add_f32_e32 v8, v8, v9
	ds_bpermute_b32 v9, v128, v8
	s_waitcnt lgkmcnt(0)
	v_add_f32_e32 v10, v8, v9
	ds_bpermute_b32 v8, v127, v18
	s_waitcnt lgkmcnt(0)
	v_add_f32_e32 v8, v18, v8
	ds_bpermute_b32 v9, v128, v8
	v_mov_b64_e32 v[16:17], v[168:169]
	v_mov_b64_e32 v[18:19], v[170:171]
	s_waitcnt lgkmcnt(0)
	v_add_f32_e32 v11, v8, v9
	v_mov_b64_e32 v[20:21], v[172:173]
	s_mov_b32 s0, 0xf800000
	v_mul_f32_e32 v8, v10, v20
	v_cmp_gt_f32_e32 vcc, s0, v8
	v_mul_f32_e32 v9, 0x4f800000, v8
	s_nop 0
	v_cndmask_b32_e32 v8, v8, v9, vcc
	v_sqrt_f32_e32 v9, v8
	s_nop 0
	v_add_u32_e32 v10, -1, v9
	v_fma_f32 v14, -v10, v9, v8
	v_cmp_ge_f32_e64 s[10:11], 0, v14
	v_add_u32_e32 v14, 1, v9
	s_nop 0
	v_cndmask_b32_e64 v10, v9, v10, s[10:11]
	v_fma_f32 v9, -v14, v9, v8
	v_cmp_lt_f32_e64 s[10:11], 0, v9
	s_nop 1
	v_cndmask_b32_e64 v9, v10, v14, s[10:11]
	v_mul_f32_e32 v10, 0x37800000, v9
	v_cndmask_b32_e32 v9, v9, v10, vcc
	v_cmp_class_f32_e32 vcc, v8, v215
	s_nop 1
	v_cndmask_b32_e32 v28, v9, v8, vcc
	v_sub_f32_e32 v20, v28, v11
	v_mov_b64_e32 v[8:9], v[176:177]
	v_mov_b64_e32 v[10:11], v[178:179]
	v_lshlrev_b32_e32 v14, 16, v8
	v_fma_f32 v22, v14, v15, 0
	v_and_b32_e32 v15, 0xffff0000, v8
	v_mul_f32_e32 v23, v15, v15
	v_fmac_f32_e32 v23, v14, v14
	v_and_b32_e32 v14, 0xffff0000, v24
	v_fmac_f32_e32 v22, v15, v14
	v_lshlrev_b32_e32 v14, 16, v9
	v_lshlrev_b32_e32 v15, 16, v25
	v_fmac_f32_e32 v23, v14, v14
	v_fmac_f32_e32 v22, v14, v15
	v_and_b32_e32 v14, 0xffff0000, v9
	v_and_b32_e32 v15, 0xffff0000, v25
	v_fmac_f32_e32 v23, v14, v14
	v_fmac_f32_e32 v22, v14, v15
	v_lshlrev_b32_e32 v14, 16, v10
	v_lshlrev_b32_e32 v15, 16, v26
	v_fmac_f32_e32 v23, v14, v14
	v_fmac_f32_e32 v22, v14, v15
	v_and_b32_e32 v14, 0xffff0000, v10
	v_and_b32_e32 v15, 0xffff0000, v26
	v_fmac_f32_e32 v23, v14, v14
	v_fmac_f32_e32 v22, v14, v15
	v_lshlrev_b32_e32 v14, 16, v11
	v_lshlrev_b32_e32 v15, 16, v27
	v_fmac_f32_e32 v23, v14, v14
	v_fmac_f32_e32 v22, v14, v15
	v_and_b32_e32 v14, 0xffff0000, v11
	v_and_b32_e32 v15, 0xffff0000, v27
	v_fmac_f32_e32 v23, v14, v14
	v_fmac_f32_e32 v22, v14, v15
	v_mov_b64_e32 v[12:13], v[180:181]
	v_mov_b64_e32 v[14:15], v[182:183]
	v_lshlrev_b32_e32 v25, 16, v16
	v_and_b32_e32 v16, 0xffff0000, v16
	s_waitcnt lgkmcnt(0)
	s_barrier
	s_waitcnt vmcnt(0)
	v_lshlrev_b32_e32 v24, 16, v12
	v_fmac_f32_e32 v23, v24, v24
	v_fmac_f32_e32 v22, v24, v25
	v_and_b32_e32 v24, 0xffff0000, v12
	v_fmac_f32_e32 v23, v24, v24
	v_fmac_f32_e32 v22, v24, v16
	v_lshlrev_b32_e32 v16, 16, v17
	v_and_b32_e32 v25, 0xffff0000, v13
	v_lshlrev_b32_e32 v24, 16, v13
	v_pk_mul_f32 v[26:27], v[24:25], v[24:25]
	v_fmac_f32_e32 v22, v24, v16
	v_and_b32_e32 v16, 0xffff0000, v17
	v_add_f32_e32 v23, v23, v26
	v_fmac_f32_e32 v22, v25, v16
	v_lshlrev_b32_e32 v26, 16, v18
	v_and_b32_e32 v17, 0xffff0000, v14
	v_lshlrev_b32_e32 v16, 16, v14
	v_add_f32_e32 v23, v23, v27
	v_pk_mul_f32 v[24:25], v[16:17], v[16:17]
	v_fmac_f32_e32 v22, v16, v26
	v_and_b32_e32 v16, 0xffff0000, v18
	v_add_f32_e32 v23, v23, v24
	v_fmac_f32_e32 v22, v17, v16
	v_and_b32_e32 v17, 0xffff0000, v15
	v_lshlrev_b32_e32 v16, 16, v15
	v_add_f32_e32 v23, v23, v25
	v_pk_mul_f32 v[24:25], v[16:17], v[16:17]
	v_lshlrev_b32_e32 v18, 16, v19
	v_add_f32_e32 v23, v23, v24
	v_fmac_f32_e32 v22, v16, v18
	v_add_f32_e32 v16, v23, v25
	v_and_b32_e32 v18, 0xffff0000, v19
	v_fmac_f32_e32 v22, v17, v18
	ds_bpermute_b32 v17, v127, v16
	s_waitcnt lgkmcnt(0)
	v_add_f32_e32 v16, v16, v17
	ds_bpermute_b32 v17, v128, v16
	s_waitcnt lgkmcnt(0)
	v_add_f32_e32 v16, v16, v17
	ds_bpermute_b32 v17, v127, v22
	v_mul_f32_e32 v16, v16, v21
	v_cmp_gt_f32_e32 vcc, s0, v16
	s_waitcnt lgkmcnt(0)
	v_add_f32_e32 v17, v22, v17
	ds_bpermute_b32 v18, v128, v17
	s_waitcnt lgkmcnt(0)
	v_add_f32_e32 v17, v17, v18
	v_mul_f32_e32 v18, 0x4f800000, v16
	v_cndmask_b32_e32 v16, v16, v18, vcc
	v_sqrt_f32_e32 v18, v16
	s_nop 0
	v_add_u32_e32 v19, -1, v18
	v_fma_f32 v21, -v19, v18, v16
	v_cmp_ge_f32_e64 s[10:11], 0, v21
	v_add_u32_e32 v21, 1, v18
	s_nop 0
	v_cndmask_b32_e64 v19, v18, v19, s[10:11]
	v_fma_f32 v18, -v21, v18, v16
	v_cmp_lt_f32_e64 s[10:11], 0, v18
	s_nop 1
	v_cndmask_b32_e64 v18, v19, v21, s[10:11]
	v_mul_f32_e32 v19, 0x37800000, v18
	v_cndmask_b32_e32 v18, v18, v19, vcc
	v_cmp_class_f32_e32 vcc, v16, v215
	s_nop 1
	v_cndmask_b32_e32 v29, v18, v16, vcc
	v_sub_f32_e32 v16, v29, v17
	v_max3_f32 v16, v20, 0, v16
	ds_bpermute_b32 v17, v129, v16
	s_waitcnt lgkmcnt(0)
	v_max_f32_e32 v17, v17, v17
	v_max_f32_e32 v16, v16, v17
	ds_bpermute_b32 v17, v130, v16
	s_waitcnt lgkmcnt(0)
	v_max_f32_e32 v17, v17, v17
	v_max_f32_e32 v16, v16, v17
	ds_bpermute_b32 v17, v131, v16
	s_waitcnt lgkmcnt(0)
	v_max_f32_e32 v17, v17, v17
	v_max_f32_e32 v16, v16, v17
	ds_bpermute_b32 v17, v132, v16
	s_and_saveexec_b64 s[0:1], s[8:9]
	s_cbranch_execz .LBB0_356
	s_waitcnt lgkmcnt(0)
	v_max_f32_e32 v17, v17, v17
	v_max_f32_e32 v16, v16, v16
	v_max_f32_e32 v16, v16, v17
	v_mov_b32_e32 v17, s43
	ds_write_b32 v17, v16
